# LN1 row loop rewritten like LN2: gamma/beta hoisted, two row buffers, counted waits, DPP row_bcast reductions
# speedup vs baseline: 1.0163x; 1.0071x over previous
.LBB0_1029:
	v_mov_b32_e32 v128, v176
	s_waitcnt vmcnt(0) lgkmcnt(0)
	s_barrier
	s_nop 4
	v_cvt_pk_bf16_f32 v80, v80, v81
	v_and_b32_e32 v129, 0xc0, v128
	v_and_b32_e32 v130, 31, v128
	v_lshrrev_b32_e32 v131, 1, v128
	v_lshrrev_b32_e32 v128, 2, v128
	v_and_b32_e32 v128, 8, v128
	v_and_or_b32 v130, v131, s93, v130
	v_lshl_or_b32 v128, v129, 1, v128
	v_mad_u64_u32 v[128:129], s[66:67], v130, s0, v[128:129]
	v_cvt_pk_bf16_f32 v81, v82, v83
	v_cvt_pk_bf16_f32 v82, v84, v85
	v_cvt_pk_bf16_f32 v83, v86, v87
	v_add_u32_e32 v84, 0x4000, v128
	v_cvt_pk_bf16_f32 v48, v48, v49
	v_cvt_pk_bf16_f32 v49, v50, v51
	v_cvt_pk_bf16_f32 v50, v52, v53
	v_cvt_pk_bf16_f32 v51, v54, v55
	v_add_u32_e32 v52, 0x8000, v128
	v_cvt_pk_bf16_f32 v16, v16, v17
	v_cvt_pk_bf16_f32 v17, v18, v19
	v_cvt_pk_bf16_f32 v18, v20, v21
	v_cvt_pk_bf16_f32 v19, v22, v23
	ds_write2_b64 v128, v[80:81], v[82:83] offset0:8 offset1:10
	v_cvt_pk_bf16_f32 v80, v88, v89
	v_cvt_pk_bf16_f32 v81, v90, v91
	v_cvt_pk_bf16_f32 v82, v92, v93
	v_cvt_pk_bf16_f32 v83, v94, v95
	ds_write2_b64 v84, v[48:49], v[50:51] offset0:72 offset1:74
	v_cvt_pk_bf16_f32 v48, v56, v57
	v_cvt_pk_bf16_f32 v49, v58, v59
	v_cvt_pk_bf16_f32 v50, v60, v61
	v_cvt_pk_bf16_f32 v51, v62, v63
	ds_write2_b64 v52, v[16:17], v[18:19] offset0:136 offset1:138
	v_cvt_pk_bf16_f32 v16, v24, v25
	v_cvt_pk_bf16_f32 v17, v26, v27
	v_cvt_pk_bf16_f32 v18, v28, v29
	v_cvt_pk_bf16_f32 v19, v30, v31
	v_add_u32_e32 v20, 0xc000, v128
	v_cvt_pk_bf16_f32 v0, v0, v1
	v_cvt_pk_bf16_f32 v1, v2, v3
	v_cvt_pk_bf16_f32 v2, v4, v5
	v_cvt_pk_bf16_f32 v3, v6, v7
	v_cvt_pk_bf16_f32 v112, v112, v113
	v_cvt_pk_bf16_f32 v113, v114, v115
	v_cvt_pk_bf16_f32 v114, v116, v117
	v_cvt_pk_bf16_f32 v115, v118, v119
	ds_write2_b64 v128, v[80:81], v[82:83] offset0:12 offset1:14
	v_cvt_pk_bf16_f32 v80, v96, v97
	v_cvt_pk_bf16_f32 v81, v98, v99
	v_cvt_pk_bf16_f32 v82, v100, v101
	v_cvt_pk_bf16_f32 v83, v102, v103
	ds_write2_b64 v84, v[48:49], v[50:51] offset0:76 offset1:78
	v_cvt_pk_bf16_f32 v48, v64, v65
	v_cvt_pk_bf16_f32 v49, v66, v67
	v_cvt_pk_bf16_f32 v50, v68, v69
	v_cvt_pk_bf16_f32 v51, v70, v71
	ds_write2_b64 v52, v[16:17], v[18:19] offset0:140 offset1:142
	v_cvt_pk_bf16_f32 v16, v32, v33
	v_cvt_pk_bf16_f32 v17, v34, v35
	v_cvt_pk_bf16_f32 v18, v36, v37
	v_cvt_pk_bf16_f32 v19, v38, v39
	ds_write2_b64 v20, v[0:1], v[2:3] offset0:200 offset1:202
	v_cvt_pk_bf16_f32 v0, v8, v9
	v_cvt_pk_bf16_f32 v1, v10, v11
	v_cvt_pk_bf16_f32 v2, v12, v13
	v_cvt_pk_bf16_f32 v3, v14, v15
	ds_write2_b64 v128, v[112:113], v[114:115] offset1:2
	v_cvt_pk_bf16_f32 v112, v120, v121
	v_cvt_pk_bf16_f32 v113, v122, v123
	v_cvt_pk_bf16_f32 v114, v124, v125
	v_cvt_pk_bf16_f32 v115, v126, v127
	ds_write2_b64 v84, v[80:81], v[82:83] offset0:64 offset1:66
	v_cvt_pk_bf16_f32 v80, v104, v105
	v_cvt_pk_bf16_f32 v81, v106, v107
	v_cvt_pk_bf16_f32 v82, v108, v109
	v_cvt_pk_bf16_f32 v83, v110, v111
	ds_write2_b64 v52, v[48:49], v[50:51] offset0:128 offset1:130
	v_cvt_pk_bf16_f32 v48, v72, v73
	v_cvt_pk_bf16_f32 v49, v74, v75
	v_cvt_pk_bf16_f32 v50, v76, v77
	v_cvt_pk_bf16_f32 v51, v78, v79
	ds_write2_b64 v20, v[16:17], v[18:19] offset0:192 offset1:194
	v_cvt_pk_bf16_f32 v16, v40, v41
	v_cvt_pk_bf16_f32 v17, v42, v43
	v_cvt_pk_bf16_f32 v18, v44, v45
	v_cvt_pk_bf16_f32 v19, v46, v47
	ds_write2_b64 v20, v[0:1], v[2:3] offset0:204 offset1:206
	v_mov_b32_e32 v1, v176
	ds_write2_b64 v128, v[112:113], v[114:115] offset0:4 offset1:6
	ds_write2_b64 v84, v[80:81], v[82:83] offset0:68 offset1:70
	ds_write2_b64 v52, v[48:49], v[50:51] offset0:132 offset1:134
	ds_write2_b64 v20, v[16:17], v[18:19] offset0:196 offset1:198
	s_waitcnt lgkmcnt(0)
	s_barrier
	v_mov_b32_e32 v1, v176
	s_mov_b32 s98, 0xffff0000
	v_lshlrev_b32_e32 v0, 4, v1
	v_and_b32_e32 v0, 0x1f0, v0
	v_lshrrev_b32_e32 v2, 5, v1
	v_mov_b32_e32 v6, 0x210
	v_mad_u32_u24 v4, v2, v6, v0
	v_add_u32_e32 v5, 0x10800, v4
	v_lshlrev_b32_e32 v6, 3, v1
	v_and_b32_e32 v6, 0xf8, v6
	v_lshl_or_b32 v132, s70, 8, v6
	v_lshlrev_b32_e32 v3, 1, v132
	v_lshl_add_u32 v3, v2, 11, v3
	v_lshlrev_b32_e32 v20, 2, v132
	v_lshl_add_u32 v20, v2, 12, v20
	v_add_u32_e32 v6, 0x0, v3
	global_load_dwordx4 v[32:35], v6, s[52:53]
	ds_read_b128 v[96:99], v4
	v_add_u32_e32 v6, 0x8000, v3
	global_load_dwordx4 v[36:39], v6, s[52:53]
	ds_read_b128 v[100:103], v4 offset:8448
	v_add_u32_e32 v6, 0x10000, v3
	global_load_dwordx4 v[40:43], v6, s[52:53]
	ds_read_b128 v[104:107], v4 offset:16896
	v_add_u32_e32 v6, 0x18000, v3
	global_load_dwordx4 v[44:47], v6, s[52:53]
	ds_read_b128 v[108:111], v4 offset:25344
	v_add_u32_e32 v6, 0x20000, v3
	global_load_dwordx4 v[48:51], v6, s[52:53]
	ds_read_b128 v[112:115], v4 offset:33792
	v_add_u32_e32 v6, 0x28000, v3
	global_load_dwordx4 v[52:55], v6, s[52:53]
	ds_read_b128 v[116:119], v4 offset:42240
	v_add_u32_e32 v6, 0x30000, v3
	global_load_dwordx4 v[56:59], v6, s[52:53]
	ds_read_b128 v[120:123], v4 offset:50688
	v_add_u32_e32 v6, 0x38000, v3
	global_load_dwordx4 v[60:63], v6, s[52:53]
	ds_read_b128 v[124:127], v4 offset:59136
	v_add_u32_e32 v6, 0x40000, v3
	global_load_dwordx4 v[64:67], v6, s[52:53]
	v_add_u32_e32 v6, 0x48000, v3
	global_load_dwordx4 v[68:71], v6, s[52:53]
	v_add_u32_e32 v6, 0x50000, v3
	global_load_dwordx4 v[72:75], v6, s[52:53]
	v_add_u32_e32 v6, 0x58000, v3
	global_load_dwordx4 v[76:79], v6, s[52:53]
	v_add_u32_e32 v6, 0x60000, v3
	global_load_dwordx4 v[80:83], v6, s[52:53]
	v_add_u32_e32 v6, 0x68000, v3
	global_load_dwordx4 v[84:87], v6, s[52:53]
	v_add_u32_e32 v6, 0x70000, v3
	global_load_dwordx4 v[88:91], v6, s[52:53]
	v_add_u32_e32 v6, 0x78000, v3
	global_load_dwordx4 v[92:95], v6, s[52:53]
	s_waitcnt vmcnt(15) lgkmcnt(7)
	v_lshlrev_b32_e32 v8, 16, v32
	v_and_b32_e32 v9, s98, v32
	v_lshlrev_b32_e32 v10, 16, v33
	v_and_b32_e32 v11, s98, v33
	v_lshlrev_b32_e32 v12, 16, v34
	v_and_b32_e32 v13, s98, v34
	v_lshlrev_b32_e32 v14, 16, v35
	v_and_b32_e32 v15, s98, v35
	v_lshlrev_b32_e32 v22, 16, v96
	v_and_b32_e32 v23, s98, v96
	v_lshlrev_b32_e32 v24, 16, v97
	v_and_b32_e32 v25, s98, v97
	v_lshlrev_b32_e32 v26, 16, v98
	v_and_b32_e32 v27, s98, v98
	v_lshlrev_b32_e32 v28, 16, v99
	v_and_b32_e32 v29, s98, v99
	v_pk_fma_f32 v[22:23], v[8:9], s[38:39], v[22:23] op_sel_hi:[1,0,1]
	v_pk_fma_f32 v[24:25], v[10:11], s[38:39], v[24:25] op_sel_hi:[1,0,1]
	v_pk_fma_f32 v[26:27], v[12:13], s[38:39], v[26:27] op_sel_hi:[1,0,1]
	v_pk_fma_f32 v[28:29], v[14:15], s[38:39], v[28:29] op_sel_hi:[1,0,1]
	ds_read_b128 v[96:99], v5
	v_add_u32_e32 v7, 0x0, v20
	global_store_dwordx4 v7, v[22:25], s[64:65]
	global_store_dwordx4 v7, v[26:29], s[64:65] offset:16
	s_waitcnt vmcnt(16) lgkmcnt(7)
	v_lshlrev_b32_e32 v8, 16, v36
	v_and_b32_e32 v9, s98, v36
	v_lshlrev_b32_e32 v10, 16, v37
	v_and_b32_e32 v11, s98, v37
	v_lshlrev_b32_e32 v12, 16, v38
	v_and_b32_e32 v13, s98, v38
	v_lshlrev_b32_e32 v14, 16, v39
	v_and_b32_e32 v15, s98, v39
	v_lshlrev_b32_e32 v22, 16, v100
	v_and_b32_e32 v23, s98, v100
	v_lshlrev_b32_e32 v24, 16, v101
	v_and_b32_e32 v25, s98, v101
	v_lshlrev_b32_e32 v26, 16, v102
	v_and_b32_e32 v27, s98, v102
	v_lshlrev_b32_e32 v28, 16, v103
	v_and_b32_e32 v29, s98, v103
	v_pk_fma_f32 v[22:23], v[8:9], s[38:39], v[22:23] op_sel_hi:[1,0,1]
	v_pk_fma_f32 v[24:25], v[10:11], s[38:39], v[24:25] op_sel_hi:[1,0,1]
	v_pk_fma_f32 v[26:27], v[12:13], s[38:39], v[26:27] op_sel_hi:[1,0,1]
	v_pk_fma_f32 v[28:29], v[14:15], s[38:39], v[28:29] op_sel_hi:[1,0,1]
	ds_read_b128 v[100:103], v5 offset:8448
	v_add_u32_e32 v7, 0x10000, v20
	global_store_dwordx4 v7, v[22:25], s[64:65]
	global_store_dwordx4 v7, v[26:29], s[64:65] offset:16
	s_waitcnt vmcnt(17) lgkmcnt(7)
	v_lshlrev_b32_e32 v8, 16, v40
	v_and_b32_e32 v9, s98, v40
	v_lshlrev_b32_e32 v10, 16, v41
	v_and_b32_e32 v11, s98, v41
	v_lshlrev_b32_e32 v12, 16, v42
	v_and_b32_e32 v13, s98, v42
	v_lshlrev_b32_e32 v14, 16, v43
	v_and_b32_e32 v15, s98, v43
	v_lshlrev_b32_e32 v22, 16, v104
	v_and_b32_e32 v23, s98, v104
	v_lshlrev_b32_e32 v24, 16, v105
	v_and_b32_e32 v25, s98, v105
	v_lshlrev_b32_e32 v26, 16, v106
	v_and_b32_e32 v27, s98, v106
	v_lshlrev_b32_e32 v28, 16, v107
	v_and_b32_e32 v29, s98, v107
	v_pk_fma_f32 v[22:23], v[8:9], s[38:39], v[22:23] op_sel_hi:[1,0,1]
	v_pk_fma_f32 v[24:25], v[10:11], s[38:39], v[24:25] op_sel_hi:[1,0,1]
	v_pk_fma_f32 v[26:27], v[12:13], s[38:39], v[26:27] op_sel_hi:[1,0,1]
	v_pk_fma_f32 v[28:29], v[14:15], s[38:39], v[28:29] op_sel_hi:[1,0,1]
	ds_read_b128 v[104:107], v5 offset:16896
	v_add_u32_e32 v7, 0x20000, v20
	global_store_dwordx4 v7, v[22:25], s[64:65]
	global_store_dwordx4 v7, v[26:29], s[64:65] offset:16
	s_waitcnt vmcnt(18) lgkmcnt(7)
	v_lshlrev_b32_e32 v8, 16, v44
	v_and_b32_e32 v9, s98, v44
	v_lshlrev_b32_e32 v10, 16, v45
	v_and_b32_e32 v11, s98, v45
	v_lshlrev_b32_e32 v12, 16, v46
	v_and_b32_e32 v13, s98, v46
	v_lshlrev_b32_e32 v14, 16, v47
	v_and_b32_e32 v15, s98, v47
	v_lshlrev_b32_e32 v22, 16, v108
	v_and_b32_e32 v23, s98, v108
	v_lshlrev_b32_e32 v24, 16, v109
	v_and_b32_e32 v25, s98, v109
	v_lshlrev_b32_e32 v26, 16, v110
	v_and_b32_e32 v27, s98, v110
	v_lshlrev_b32_e32 v28, 16, v111
	v_and_b32_e32 v29, s98, v111
	v_pk_fma_f32 v[22:23], v[8:9], s[38:39], v[22:23] op_sel_hi:[1,0,1]
	v_pk_fma_f32 v[24:25], v[10:11], s[38:39], v[24:25] op_sel_hi:[1,0,1]
	v_pk_fma_f32 v[26:27], v[12:13], s[38:39], v[26:27] op_sel_hi:[1,0,1]
	v_pk_fma_f32 v[28:29], v[14:15], s[38:39], v[28:29] op_sel_hi:[1,0,1]
	ds_read_b128 v[108:111], v5 offset:25344
	v_add_u32_e32 v7, 0x30000, v20
	global_store_dwordx4 v7, v[22:25], s[64:65]
	global_store_dwordx4 v7, v[26:29], s[64:65] offset:16
	s_waitcnt vmcnt(19) lgkmcnt(7)
	v_lshlrev_b32_e32 v8, 16, v48
	v_and_b32_e32 v9, s98, v48
	v_lshlrev_b32_e32 v10, 16, v49
	v_and_b32_e32 v11, s98, v49
	v_lshlrev_b32_e32 v12, 16, v50
	v_and_b32_e32 v13, s98, v50
	v_lshlrev_b32_e32 v14, 16, v51
	v_and_b32_e32 v15, s98, v51
	v_lshlrev_b32_e32 v22, 16, v112
	v_and_b32_e32 v23, s98, v112
	v_lshlrev_b32_e32 v24, 16, v113
	v_and_b32_e32 v25, s98, v113
	v_lshlrev_b32_e32 v26, 16, v114
	v_and_b32_e32 v27, s98, v114
	v_lshlrev_b32_e32 v28, 16, v115
	v_and_b32_e32 v29, s98, v115
	v_pk_fma_f32 v[22:23], v[8:9], s[38:39], v[22:23] op_sel_hi:[1,0,1]
	v_pk_fma_f32 v[24:25], v[10:11], s[38:39], v[24:25] op_sel_hi:[1,0,1]
	v_pk_fma_f32 v[26:27], v[12:13], s[38:39], v[26:27] op_sel_hi:[1,0,1]
	v_pk_fma_f32 v[28:29], v[14:15], s[38:39], v[28:29] op_sel_hi:[1,0,1]
	ds_read_b128 v[112:115], v5 offset:33792
	v_add_u32_e32 v7, 0x40000, v20
	global_store_dwordx4 v7, v[22:25], s[64:65]
	global_store_dwordx4 v7, v[26:29], s[64:65] offset:16
	s_waitcnt vmcnt(20) lgkmcnt(7)
	v_lshlrev_b32_e32 v8, 16, v52
	v_and_b32_e32 v9, s98, v52
	v_lshlrev_b32_e32 v10, 16, v53
	v_and_b32_e32 v11, s98, v53
	v_lshlrev_b32_e32 v12, 16, v54
	v_and_b32_e32 v13, s98, v54
	v_lshlrev_b32_e32 v14, 16, v55
	v_and_b32_e32 v15, s98, v55
	v_lshlrev_b32_e32 v22, 16, v116
	v_and_b32_e32 v23, s98, v116
	v_lshlrev_b32_e32 v24, 16, v117
	v_and_b32_e32 v25, s98, v117
	v_lshlrev_b32_e32 v26, 16, v118
	v_and_b32_e32 v27, s98, v118
	v_lshlrev_b32_e32 v28, 16, v119
	v_and_b32_e32 v29, s98, v119
	v_pk_fma_f32 v[22:23], v[8:9], s[38:39], v[22:23] op_sel_hi:[1,0,1]
	v_pk_fma_f32 v[24:25], v[10:11], s[38:39], v[24:25] op_sel_hi:[1,0,1]
	v_pk_fma_f32 v[26:27], v[12:13], s[38:39], v[26:27] op_sel_hi:[1,0,1]
	v_pk_fma_f32 v[28:29], v[14:15], s[38:39], v[28:29] op_sel_hi:[1,0,1]
	ds_read_b128 v[116:119], v5 offset:42240
	v_add_u32_e32 v7, 0x50000, v20
	global_store_dwordx4 v7, v[22:25], s[64:65]
	global_store_dwordx4 v7, v[26:29], s[64:65] offset:16
	s_waitcnt vmcnt(21) lgkmcnt(7)
	v_lshlrev_b32_e32 v8, 16, v56
	v_and_b32_e32 v9, s98, v56
	v_lshlrev_b32_e32 v10, 16, v57
	v_and_b32_e32 v11, s98, v57
	v_lshlrev_b32_e32 v12, 16, v58
	v_and_b32_e32 v13, s98, v58
	v_lshlrev_b32_e32 v14, 16, v59
	v_and_b32_e32 v15, s98, v59
	v_lshlrev_b32_e32 v22, 16, v120
	v_and_b32_e32 v23, s98, v120
	v_lshlrev_b32_e32 v24, 16, v121
	v_and_b32_e32 v25, s98, v121
	v_lshlrev_b32_e32 v26, 16, v122
	v_and_b32_e32 v27, s98, v122
	v_lshlrev_b32_e32 v28, 16, v123
	v_and_b32_e32 v29, s98, v123
	v_pk_fma_f32 v[22:23], v[8:9], s[38:39], v[22:23] op_sel_hi:[1,0,1]
	v_pk_fma_f32 v[24:25], v[10:11], s[38:39], v[24:25] op_sel_hi:[1,0,1]
	v_pk_fma_f32 v[26:27], v[12:13], s[38:39], v[26:27] op_sel_hi:[1,0,1]
	v_pk_fma_f32 v[28:29], v[14:15], s[38:39], v[28:29] op_sel_hi:[1,0,1]
	ds_read_b128 v[120:123], v5 offset:50688
	v_add_u32_e32 v7, 0x60000, v20
	global_store_dwordx4 v7, v[22:25], s[64:65]
	global_store_dwordx4 v7, v[26:29], s[64:65] offset:16
	s_waitcnt vmcnt(22) lgkmcnt(7)
	v_lshlrev_b32_e32 v8, 16, v60
	v_and_b32_e32 v9, s98, v60
	v_lshlrev_b32_e32 v10, 16, v61
	v_and_b32_e32 v11, s98, v61
	v_lshlrev_b32_e32 v12, 16, v62
	v_and_b32_e32 v13, s98, v62
	v_lshlrev_b32_e32 v14, 16, v63
	v_and_b32_e32 v15, s98, v63
	v_lshlrev_b32_e32 v22, 16, v124
	v_and_b32_e32 v23, s98, v124
	v_lshlrev_b32_e32 v24, 16, v125
	v_and_b32_e32 v25, s98, v125
	v_lshlrev_b32_e32 v26, 16, v126
	v_and_b32_e32 v27, s98, v126
	v_lshlrev_b32_e32 v28, 16, v127
	v_and_b32_e32 v29, s98, v127
	v_pk_fma_f32 v[22:23], v[8:9], s[38:39], v[22:23] op_sel_hi:[1,0,1]
	v_pk_fma_f32 v[24:25], v[10:11], s[38:39], v[24:25] op_sel_hi:[1,0,1]
	v_pk_fma_f32 v[26:27], v[12:13], s[38:39], v[26:27] op_sel_hi:[1,0,1]
	v_pk_fma_f32 v[28:29], v[14:15], s[38:39], v[28:29] op_sel_hi:[1,0,1]
	ds_read_b128 v[124:127], v5 offset:59136
	v_add_u32_e32 v7, 0x70000, v20
	global_store_dwordx4 v7, v[22:25], s[64:65]
	global_store_dwordx4 v7, v[26:29], s[64:65] offset:16
	s_waitcnt vmcnt(23) lgkmcnt(7)
	v_lshlrev_b32_e32 v8, 16, v64
	v_and_b32_e32 v9, s98, v64
	v_lshlrev_b32_e32 v10, 16, v65
	v_and_b32_e32 v11, s98, v65
	v_lshlrev_b32_e32 v12, 16, v66
	v_and_b32_e32 v13, s98, v66
	v_lshlrev_b32_e32 v14, 16, v67
	v_and_b32_e32 v15, s98, v67
	v_lshlrev_b32_e32 v22, 16, v96
	v_and_b32_e32 v23, s98, v96
	v_lshlrev_b32_e32 v24, 16, v97
	v_and_b32_e32 v25, s98, v97
	v_lshlrev_b32_e32 v26, 16, v98
	v_and_b32_e32 v27, s98, v98
	v_lshlrev_b32_e32 v28, 16, v99
	v_and_b32_e32 v29, s98, v99
	v_pk_fma_f32 v[22:23], v[8:9], s[38:39], v[22:23] op_sel_hi:[1,0,1]
	v_pk_fma_f32 v[24:25], v[10:11], s[38:39], v[24:25] op_sel_hi:[1,0,1]
	v_pk_fma_f32 v[26:27], v[12:13], s[38:39], v[26:27] op_sel_hi:[1,0,1]
	v_pk_fma_f32 v[28:29], v[14:15], s[38:39], v[28:29] op_sel_hi:[1,0,1]
	v_add_u32_e32 v7, 0x80000, v20
	global_store_dwordx4 v7, v[22:25], s[64:65]
	global_store_dwordx4 v7, v[26:29], s[64:65] offset:16
	s_waitcnt vmcnt(24) lgkmcnt(6)
	v_lshlrev_b32_e32 v8, 16, v68
	v_and_b32_e32 v9, s98, v68
	v_lshlrev_b32_e32 v10, 16, v69
	v_and_b32_e32 v11, s98, v69
	v_lshlrev_b32_e32 v12, 16, v70
	v_and_b32_e32 v13, s98, v70
	v_lshlrev_b32_e32 v14, 16, v71
	v_and_b32_e32 v15, s98, v71
	v_lshlrev_b32_e32 v22, 16, v100
	v_and_b32_e32 v23, s98, v100
	v_lshlrev_b32_e32 v24, 16, v101
	v_and_b32_e32 v25, s98, v101
	v_lshlrev_b32_e32 v26, 16, v102
	v_and_b32_e32 v27, s98, v102
	v_lshlrev_b32_e32 v28, 16, v103
	v_and_b32_e32 v29, s98, v103
	v_pk_fma_f32 v[22:23], v[8:9], s[38:39], v[22:23] op_sel_hi:[1,0,1]
	v_pk_fma_f32 v[24:25], v[10:11], s[38:39], v[24:25] op_sel_hi:[1,0,1]
	v_pk_fma_f32 v[26:27], v[12:13], s[38:39], v[26:27] op_sel_hi:[1,0,1]
	v_pk_fma_f32 v[28:29], v[14:15], s[38:39], v[28:29] op_sel_hi:[1,0,1]
	v_add_u32_e32 v7, 0x90000, v20
	global_store_dwordx4 v7, v[22:25], s[64:65]
	global_store_dwordx4 v7, v[26:29], s[64:65] offset:16
	s_waitcnt vmcnt(25) lgkmcnt(5)
	v_lshlrev_b32_e32 v8, 16, v72
	v_and_b32_e32 v9, s98, v72
	v_lshlrev_b32_e32 v10, 16, v73
	v_and_b32_e32 v11, s98, v73
	v_lshlrev_b32_e32 v12, 16, v74
	v_and_b32_e32 v13, s98, v74
	v_lshlrev_b32_e32 v14, 16, v75
	v_and_b32_e32 v15, s98, v75
	v_lshlrev_b32_e32 v22, 16, v104
	v_and_b32_e32 v23, s98, v104
	v_lshlrev_b32_e32 v24, 16, v105
	v_and_b32_e32 v25, s98, v105
	v_lshlrev_b32_e32 v26, 16, v106
	v_and_b32_e32 v27, s98, v106
	v_lshlrev_b32_e32 v28, 16, v107
	v_and_b32_e32 v29, s98, v107
	v_pk_fma_f32 v[22:23], v[8:9], s[38:39], v[22:23] op_sel_hi:[1,0,1]
	v_pk_fma_f32 v[24:25], v[10:11], s[38:39], v[24:25] op_sel_hi:[1,0,1]
	v_pk_fma_f32 v[26:27], v[12:13], s[38:39], v[26:27] op_sel_hi:[1,0,1]
	v_pk_fma_f32 v[28:29], v[14:15], s[38:39], v[28:29] op_sel_hi:[1,0,1]
	v_add_u32_e32 v7, 0xa0000, v20
	global_store_dwordx4 v7, v[22:25], s[64:65]
	global_store_dwordx4 v7, v[26:29], s[64:65] offset:16
	s_waitcnt vmcnt(26) lgkmcnt(4)
	v_lshlrev_b32_e32 v8, 16, v76
	v_and_b32_e32 v9, s98, v76
	v_lshlrev_b32_e32 v10, 16, v77
	v_and_b32_e32 v11, s98, v77
	v_lshlrev_b32_e32 v12, 16, v78
	v_and_b32_e32 v13, s98, v78
	v_lshlrev_b32_e32 v14, 16, v79
	v_and_b32_e32 v15, s98, v79
	v_lshlrev_b32_e32 v22, 16, v108
	v_and_b32_e32 v23, s98, v108
	v_lshlrev_b32_e32 v24, 16, v109
	v_and_b32_e32 v25, s98, v109
	v_lshlrev_b32_e32 v26, 16, v110
	v_and_b32_e32 v27, s98, v110
	v_lshlrev_b32_e32 v28, 16, v111
	v_and_b32_e32 v29, s98, v111
	v_pk_fma_f32 v[22:23], v[8:9], s[38:39], v[22:23] op_sel_hi:[1,0,1]
	v_pk_fma_f32 v[24:25], v[10:11], s[38:39], v[24:25] op_sel_hi:[1,0,1]
	v_pk_fma_f32 v[26:27], v[12:13], s[38:39], v[26:27] op_sel_hi:[1,0,1]
	v_pk_fma_f32 v[28:29], v[14:15], s[38:39], v[28:29] op_sel_hi:[1,0,1]
	v_add_u32_e32 v7, 0xb0000, v20
	global_store_dwordx4 v7, v[22:25], s[64:65]
	global_store_dwordx4 v7, v[26:29], s[64:65] offset:16
	s_waitcnt vmcnt(27) lgkmcnt(3)
	v_lshlrev_b32_e32 v8, 16, v80
	v_and_b32_e32 v9, s98, v80
	v_lshlrev_b32_e32 v10, 16, v81
	v_and_b32_e32 v11, s98, v81
	v_lshlrev_b32_e32 v12, 16, v82
	v_and_b32_e32 v13, s98, v82
	v_lshlrev_b32_e32 v14, 16, v83
	v_and_b32_e32 v15, s98, v83
	v_lshlrev_b32_e32 v22, 16, v112
	v_and_b32_e32 v23, s98, v112
	v_lshlrev_b32_e32 v24, 16, v113
	v_and_b32_e32 v25, s98, v113
	v_lshlrev_b32_e32 v26, 16, v114
	v_and_b32_e32 v27, s98, v114
	v_lshlrev_b32_e32 v28, 16, v115
	v_and_b32_e32 v29, s98, v115
	v_pk_fma_f32 v[22:23], v[8:9], s[38:39], v[22:23] op_sel_hi:[1,0,1]
	v_pk_fma_f32 v[24:25], v[10:11], s[38:39], v[24:25] op_sel_hi:[1,0,1]
	v_pk_fma_f32 v[26:27], v[12:13], s[38:39], v[26:27] op_sel_hi:[1,0,1]
	v_pk_fma_f32 v[28:29], v[14:15], s[38:39], v[28:29] op_sel_hi:[1,0,1]
	v_add_u32_e32 v7, 0xc0000, v20
	global_store_dwordx4 v7, v[22:25], s[64:65]
	global_store_dwordx4 v7, v[26:29], s[64:65] offset:16
	s_waitcnt vmcnt(28) lgkmcnt(2)
	v_lshlrev_b32_e32 v8, 16, v84
	v_and_b32_e32 v9, s98, v84
	v_lshlrev_b32_e32 v10, 16, v85
	v_and_b32_e32 v11, s98, v85
	v_lshlrev_b32_e32 v12, 16, v86
	v_and_b32_e32 v13, s98, v86
	v_lshlrev_b32_e32 v14, 16, v87
	v_and_b32_e32 v15, s98, v87
	v_lshlrev_b32_e32 v22, 16, v116
	v_and_b32_e32 v23, s98, v116
	v_lshlrev_b32_e32 v24, 16, v117
	v_and_b32_e32 v25, s98, v117
	v_lshlrev_b32_e32 v26, 16, v118
	v_and_b32_e32 v27, s98, v118
	v_lshlrev_b32_e32 v28, 16, v119
	v_and_b32_e32 v29, s98, v119
	v_pk_fma_f32 v[22:23], v[8:9], s[38:39], v[22:23] op_sel_hi:[1,0,1]
	v_pk_fma_f32 v[24:25], v[10:11], s[38:39], v[24:25] op_sel_hi:[1,0,1]
	v_pk_fma_f32 v[26:27], v[12:13], s[38:39], v[26:27] op_sel_hi:[1,0,1]
	v_pk_fma_f32 v[28:29], v[14:15], s[38:39], v[28:29] op_sel_hi:[1,0,1]
	v_add_u32_e32 v7, 0xd0000, v20
	global_store_dwordx4 v7, v[22:25], s[64:65]
	global_store_dwordx4 v7, v[26:29], s[64:65] offset:16
	s_waitcnt vmcnt(29) lgkmcnt(1)
	v_lshlrev_b32_e32 v8, 16, v88
	v_and_b32_e32 v9, s98, v88
	v_lshlrev_b32_e32 v10, 16, v89
	v_and_b32_e32 v11, s98, v89
	v_lshlrev_b32_e32 v12, 16, v90
	v_and_b32_e32 v13, s98, v90
	v_lshlrev_b32_e32 v14, 16, v91
	v_and_b32_e32 v15, s98, v91
	v_lshlrev_b32_e32 v22, 16, v120
	v_and_b32_e32 v23, s98, v120
	v_lshlrev_b32_e32 v24, 16, v121
	v_and_b32_e32 v25, s98, v121
	v_lshlrev_b32_e32 v26, 16, v122
	v_and_b32_e32 v27, s98, v122
	v_lshlrev_b32_e32 v28, 16, v123
	v_and_b32_e32 v29, s98, v123
	v_pk_fma_f32 v[22:23], v[8:9], s[38:39], v[22:23] op_sel_hi:[1,0,1]
	v_pk_fma_f32 v[24:25], v[10:11], s[38:39], v[24:25] op_sel_hi:[1,0,1]
	v_pk_fma_f32 v[26:27], v[12:13], s[38:39], v[26:27] op_sel_hi:[1,0,1]
	v_pk_fma_f32 v[28:29], v[14:15], s[38:39], v[28:29] op_sel_hi:[1,0,1]
	v_add_u32_e32 v7, 0xe0000, v20
	global_store_dwordx4 v7, v[22:25], s[64:65]
	global_store_dwordx4 v7, v[26:29], s[64:65] offset:16
	s_waitcnt vmcnt(30) lgkmcnt(0)
	v_lshlrev_b32_e32 v8, 16, v92
	v_and_b32_e32 v9, s98, v92
	v_lshlrev_b32_e32 v10, 16, v93
	v_and_b32_e32 v11, s98, v93
	v_lshlrev_b32_e32 v12, 16, v94
	v_and_b32_e32 v13, s98, v94
	v_lshlrev_b32_e32 v14, 16, v95
	v_and_b32_e32 v15, s98, v95
	v_lshlrev_b32_e32 v22, 16, v124
	v_and_b32_e32 v23, s98, v124
	v_lshlrev_b32_e32 v24, 16, v125
	v_and_b32_e32 v25, s98, v125
	v_lshlrev_b32_e32 v26, 16, v126
	v_and_b32_e32 v27, s98, v126
	v_lshlrev_b32_e32 v28, 16, v127
	v_and_b32_e32 v29, s98, v127
	v_pk_fma_f32 v[22:23], v[8:9], s[38:39], v[22:23] op_sel_hi:[1,0,1]
	v_pk_fma_f32 v[24:25], v[10:11], s[38:39], v[24:25] op_sel_hi:[1,0,1]
	v_pk_fma_f32 v[26:27], v[12:13], s[38:39], v[26:27] op_sel_hi:[1,0,1]
	v_pk_fma_f32 v[28:29], v[14:15], s[38:39], v[28:29] op_sel_hi:[1,0,1]
	v_add_u32_e32 v7, 0xf0000, v20
	global_store_dwordx4 v7, v[22:25], s[64:65]
	global_store_dwordx4 v7, v[26:29], s[64:65] offset:16
	s_movk_i32 s66, 0x2000
	s_add_i32 s70, s70, 1
	s_add_u32 s50, s50, 0x80000
	s_addc_u32 s51, s51, 0
	s_cmp_eq_u32 s70, 4
	s_cbranch_scc0 .LBB0_1023
	s_lshl_b64 s[52:53], s[8:9], 12
	s_mov_b64 s[50:51], 0
	s_barrier
	s_add_u32 s3, s96, s50
	s_addc_u32 s16, s97, s51
	v_mov_b32_e32 v26, v176
	s_add_u32 s3, s3, s62
	v_ashrrev_i32_e32 v0, 1, v26
	s_addc_u32 s16, s16, s63
	v_and_b32_e32 v16, 0xffffffe0, v0
	s_add_u32 s54, s3, 0x18000000
	v_ashrrev_i32_e32 v17, 31, v16
	v_lshlrev_b32_e32 v2, 2, v26
	s_addc_u32 s55, s16, 0
	v_lshlrev_b64 v[24:25], 12, v[16:17]
	v_and_b32_e32 v132, 0xfc, v2
	v_lshl_add_u64 v[0:1], s[54:55], 0, v[24:25]
	v_lshlrev_b32_e32 v22, 2, v132
	v_mov_b32_e32 v23, v133
	v_lshl_add_u64 v[12:13], v[0:1], 0, v[22:23]
	global_load_dwordx4 v[0:3], v[12:13], off
	global_load_dwordx4 v[4:7], v[12:13], off offset:1024
	global_load_dwordx4 v[8:11], v[12:13], off offset:2048
	s_nop 0
	global_load_dwordx4 v[12:15], v[12:13], off offset:3072
	v_xor_b32_e32 v20, 16, v171
	v_and_b32_e32 v30, 63, v26
	v_lshlrev_b64 v[26:27], 10, v[16:17]
	v_cmp_lt_i32_e32 vcc, v20, v178
	v_lshl_add_u64 v[26:27], s[94:95], 0, v[26:27]
	v_lshlrev_b64 v[28:29], 11, v[16:17]
	v_cndmask_b32_e32 v20, v171, v20, vcc
	v_cmp_lt_i32_e32 vcc, v177, v178
	v_readlane_b32 s60, v255, 6
	v_lshl_add_u64 v[24:25], s[52:53], 0, v[24:25]
	v_lshl_add_u64 v[26:27], v[26:27], 0, v[132:133]
	v_lshl_add_u64 v[28:29], s[46:47], 0, v[28:29]
	v_lshlrev_b32_e32 v132, 3, v30
	v_lshlrev_b32_e32 v36, 2, v20
	v_cndmask_b32_e32 v20, v171, v177, vcc
	v_readlane_b32 s64, v255, 10
	v_readlane_b32 s65, v255, 11
	v_readlane_b32 s66, v255, 12
	v_readlane_b32 s67, v255, 13
	v_lshl_or_b32 v24, v30, 4, v24
	v_lshl_add_u64 v[28:29], v[28:29], 0, v[132:133]
	v_lshl_add_u64 v[18:19], s[54:55], 0, v[22:23]
	s_mov_b32 s3, 0
	v_lshlrev_b32_e32 v141, 2, v20
	v_lshl_add_u64 v[20:21], s[64:65], 0, v[22:23]
	v_lshl_add_u64 v[22:23], s[66:67], 0, v[22:23]
	v_lshl_add_u64 v[24:25], s[10:11], 0, v[24:25]
	v_lshl_add_u64 v[26:27], s[12:13], 0, v[26:27]
	v_lshl_add_u64 v[28:29], s[14:15], 0, v[28:29]
	v_readlane_b32 s61, v255, 7
	v_readlane_b32 s62, v255, 8
	v_readlane_b32 s63, v255, 9
	v_readlane_b32 s68, v255, 14
	v_readlane_b32 s69, v255, 15
	v_readlane_b32 s70, v255, 16
	v_readlane_b32 s71, v255, 17
	v_readlane_b32 s72, v255, 18
	v_readlane_b32 s73, v255, 19
	v_readlane_b32 s74, v255, 20
	v_readlane_b32 s75, v255, 21
	v_mbcnt_lo_u32_b32 v254, -1, 0
	v_mbcnt_hi_u32_b32 v254, -1, v254
	v_lshlrev_b64 v[46:47], 12, v[16:17]
	v_lshl_add_u64 v[46:47], v[18:19], 0, v[46:47]
	s_mov_b64 s[100:101], 0x1000
	v_lshl_add_u64 v[46:47], v[46:47], 0, s[100:101]
	global_load_dwordx4 v[214:217], v[20:21], off
	global_load_dwordx4 v[218:221], v[20:21], off offset:1024
	global_load_dwordx4 v[222:225], v[20:21], off offset:2048
	global_load_dwordx4 v[226:229], v[20:21], off offset:3072
	global_load_dwordx4 v[230:233], v[22:23], off
	global_load_dwordx4 v[234:237], v[22:23], off offset:1024
	global_load_dwordx4 v[238:241], v[22:23], off offset:2048
	global_load_dwordx4 v[242:245], v[22:23], off offset:3072
	global_load_dword v76, v[20:21], off
	global_load_dword v76, v[20:21], off
	global_load_dword v76, v[20:21], off
	global_load_dword v76, v[20:21], off
	global_load_dword v76, v[20:21], off
	global_load_dword v76, v[20:21], off
	global_load_dword v76, v[20:21], off
	global_load_dword v76, v[20:21], off
	v_mov_b32_e32 v44, 0x41000000
	s_mov_b32 s3, 0
.Lln1_pair:
	global_load_dwordx4 v[48:51], v[46:47], off
	global_load_dwordx4 v[52:55], v[46:47], off offset:1024
	global_load_dwordx4 v[56:59], v[46:47], off offset:2048
	global_load_dwordx4 v[60:63], v[46:47], off offset:3072
	s_waitcnt vmcnt(12)
	v_pk_add_f32 v[64:65], v[0:1], v[2:3]
	v_pk_add_f32 v[66:67], v[4:5], v[6:7]
	v_pk_add_f32 v[68:69], v[8:9], v[10:11]
	v_pk_add_f32 v[70:71], v[12:13], v[14:15]
	v_pk_add_f32 v[64:65], v[64:65], v[66:67]
	v_pk_add_f32 v[68:69], v[68:69], v[70:71]
	s_nop 0
	v_pk_add_f32 v[64:65], v[64:65], v[68:69]
	s_nop 0
	v_add_f32_e32 v64, v64, v65
	s_nop 1
	v_add_f32_dpp v64, v64, v64 quad_perm:[1,0,3,2] row_mask:0xf bank_mask:0xf bound_ctrl:1
	s_nop 1
	v_add_f32_dpp v64, v64, v64 quad_perm:[2,3,0,1] row_mask:0xf bank_mask:0xf bound_ctrl:1
	s_nop 1
	v_add_f32_dpp v64, v64, v64 row_ror:4 row_mask:0xf bank_mask:0xf bound_ctrl:1
	s_nop 1
	v_add_f32_dpp v64, v64, v64 row_ror:8 row_mask:0xf bank_mask:0xf bound_ctrl:1
	s_nop 1
	v_add_f32_dpp v64, v64, v64 row_bcast:15 row_mask:0xa bank_mask:0xf
	s_nop 1
	v_add_f32_dpp v64, v64, v64 row_bcast:31 row_mask:0xc bank_mask:0xf
	s_nop 0
	v_readlane_b32 s98, v64, 63
	v_cmp_eq_u32_e64 s[100:101], s3, v254
	s_nop 0
	v_mov_b32_e32 v66, s98
	v_mul_f32_e32 v66, 0x3a800000, v66
	s_nop 0
	v_cndmask_b32_e64 v252, v252, v66, s[100:101]
	v_pk_add_f32 v[0:1], v[0:1], v[66:67] op_sel_hi:[1,0] neg_lo:[0,1] neg_hi:[0,1]
	v_pk_add_f32 v[2:3], v[2:3], v[66:67] op_sel_hi:[1,0] neg_lo:[0,1] neg_hi:[0,1]
	v_pk_add_f32 v[4:5], v[4:5], v[66:67] op_sel_hi:[1,0] neg_lo:[0,1] neg_hi:[0,1]
	v_pk_add_f32 v[6:7], v[6:7], v[66:67] op_sel_hi:[1,0] neg_lo:[0,1] neg_hi:[0,1]
	v_pk_add_f32 v[8:9], v[8:9], v[66:67] op_sel_hi:[1,0] neg_lo:[0,1] neg_hi:[0,1]
	v_pk_add_f32 v[10:11], v[10:11], v[66:67] op_sel_hi:[1,0] neg_lo:[0,1] neg_hi:[0,1]
	v_pk_add_f32 v[12:13], v[12:13], v[66:67] op_sel_hi:[1,0] neg_lo:[0,1] neg_hi:[0,1]
	v_pk_add_f32 v[14:15], v[14:15], v[66:67] op_sel_hi:[1,0] neg_lo:[0,1] neg_hi:[0,1]
	v_pk_mul_f32 v[68:69], v[0:1], v[0:1]
	v_pk_mul_f32 v[70:71], v[2:3], v[2:3]
	v_pk_fma_f32 v[68:69], v[4:5], v[4:5], v[68:69]
	v_pk_fma_f32 v[70:71], v[6:7], v[6:7], v[70:71]
	v_pk_fma_f32 v[68:69], v[8:9], v[8:9], v[68:69]
	v_pk_fma_f32 v[70:71], v[10:11], v[10:11], v[70:71]
	v_pk_fma_f32 v[68:69], v[12:13], v[12:13], v[68:69]
	v_pk_fma_f32 v[70:71], v[14:15], v[14:15], v[70:71]
	s_nop 0
	v_pk_add_f32 v[68:69], v[68:69], v[70:71]
	s_nop 0
	v_add_f32_e32 v68, v68, v69
	s_nop 1
	v_add_f32_dpp v68, v68, v68 quad_perm:[1,0,3,2] row_mask:0xf bank_mask:0xf bound_ctrl:1
	s_nop 1
	v_add_f32_dpp v68, v68, v68 quad_perm:[2,3,0,1] row_mask:0xf bank_mask:0xf bound_ctrl:1
	s_nop 1
	v_add_f32_dpp v68, v68, v68 row_ror:4 row_mask:0xf bank_mask:0xf bound_ctrl:1
	s_nop 1
	v_add_f32_dpp v68, v68, v68 row_ror:8 row_mask:0xf bank_mask:0xf bound_ctrl:1
	s_nop 1
	v_add_f32_dpp v68, v68, v68 row_bcast:15 row_mask:0xa bank_mask:0xf
	s_nop 1
	v_add_f32_dpp v68, v68, v68 row_bcast:31 row_mask:0xc bank_mask:0xf
	s_nop 0
	v_readlane_b32 s99, v68, 63
	s_nop 1
	v_mov_b32_e32 v70, s99
	v_fmamk_f32 v70, v70, 0x3a800000, v138
	v_rsq_f32_e32 v70, v70
	s_nop 0
	v_cndmask_b32_e64 v253, v253, v70, s[100:101]
	v_pk_mul_f32 v[0:1], v[0:1], v[70:71] op_sel_hi:[1,0]
	v_pk_mul_f32 v[2:3], v[2:3], v[70:71] op_sel_hi:[1,0]
	v_pk_mul_f32 v[4:5], v[4:5], v[70:71] op_sel_hi:[1,0]
	v_pk_mul_f32 v[6:7], v[6:7], v[70:71] op_sel_hi:[1,0]
	v_pk_mul_f32 v[8:9], v[8:9], v[70:71] op_sel_hi:[1,0]
	v_pk_mul_f32 v[10:11], v[10:11], v[70:71] op_sel_hi:[1,0]
	v_pk_mul_f32 v[12:13], v[12:13], v[70:71] op_sel_hi:[1,0]
	v_pk_mul_f32 v[14:15], v[14:15], v[70:71] op_sel_hi:[1,0]
	v_pk_fma_f32 v[0:1], v[214:215], v[0:1], v[230:231]
	v_pk_fma_f32 v[2:3], v[216:217], v[2:3], v[232:233]
	v_pk_fma_f32 v[4:5], v[218:219], v[4:5], v[234:235]
	v_pk_fma_f32 v[6:7], v[220:221], v[6:7], v[236:237]
	v_pk_fma_f32 v[8:9], v[222:223], v[8:9], v[238:239]
	v_pk_fma_f32 v[10:11], v[224:225], v[10:11], v[240:241]
	v_pk_fma_f32 v[12:13], v[226:227], v[12:13], v[242:243]
	v_pk_fma_f32 v[14:15], v[228:229], v[14:15], v[244:245]
	s_nop 0
	v_cvt_pk_bf16_f32 v64, v0, v1
	v_cvt_pk_bf16_f32 v65, v2, v3
	v_pk_mul_f32 v[0:1], v[0:1], v[44:45] op_sel_hi:[1,0]
	v_pk_mul_f32 v[2:3], v[2:3], v[44:45] op_sel_hi:[1,0]
	global_store_dwordx2 v[28:29], v[64:65], off offset:-1024
	v_cvt_pk_fp8_f32 v72, v0, v1
	v_cvt_pk_fp8_f32 v72, v2, v3 op_sel:[0,0,1]
	global_store_dword v[26:27], v72, off offset:-512
	v_cvt_pk_bf16_f32 v66, v4, v5
	v_cvt_pk_bf16_f32 v67, v6, v7
	v_pk_mul_f32 v[4:5], v[4:5], v[44:45] op_sel_hi:[1,0]
	v_pk_mul_f32 v[6:7], v[6:7], v[44:45] op_sel_hi:[1,0]
	global_store_dwordx2 v[28:29], v[66:67], off offset:-512
	v_cvt_pk_fp8_f32 v73, v4, v5
	v_cvt_pk_fp8_f32 v73, v6, v7 op_sel:[0,0,1]
	global_store_dword v[26:27], v73, off offset:-256
	v_cvt_pk_bf16_f32 v68, v8, v9
	v_cvt_pk_bf16_f32 v69, v10, v11
	v_pk_mul_f32 v[8:9], v[8:9], v[44:45] op_sel_hi:[1,0]
	v_pk_mul_f32 v[10:11], v[10:11], v[44:45] op_sel_hi:[1,0]
	global_store_dwordx2 v[28:29], v[68:69], off offset:0
	v_cvt_pk_fp8_f32 v74, v8, v9
	v_cvt_pk_fp8_f32 v74, v10, v11 op_sel:[0,0,1]
	global_store_dword v[26:27], v74, off offset:0
	v_cvt_pk_bf16_f32 v70, v12, v13
	v_cvt_pk_bf16_f32 v71, v14, v15
	v_pk_mul_f32 v[12:13], v[12:13], v[44:45] op_sel_hi:[1,0]
	v_pk_mul_f32 v[14:15], v[14:15], v[44:45] op_sel_hi:[1,0]
	global_store_dwordx2 v[28:29], v[70:71], off offset:512
	v_cvt_pk_fp8_f32 v75, v12, v13
	v_cvt_pk_fp8_f32 v75, v14, v15 op_sel:[0,0,1]
	global_store_dword v[26:27], v75, off offset:256
	s_add_i32 s3, s3, 1
	s_movk_i32 s100, 0x2000
	s_cmp_lt_u32 s3, 31
	s_cselect_b32 s100, s100, 0x1000
	s_mov_b32 s101, 0
	v_lshl_add_u64 v[46:47], v[46:47], 0, s[100:101]
	global_load_dwordx4 v[0:3], v[46:47], off offset:-4096
	global_load_dwordx4 v[4:7], v[46:47], off offset:-3072
	global_load_dwordx4 v[8:11], v[46:47], off offset:-2048
	global_load_dwordx4 v[12:15], v[46:47], off offset:-1024
	s_waitcnt vmcnt(12)
	v_pk_add_f32 v[64:65], v[48:49], v[50:51]
	v_pk_add_f32 v[66:67], v[52:53], v[54:55]
	v_pk_add_f32 v[68:69], v[56:57], v[58:59]
	v_pk_add_f32 v[70:71], v[60:61], v[62:63]
	v_pk_add_f32 v[64:65], v[64:65], v[66:67]
	v_pk_add_f32 v[68:69], v[68:69], v[70:71]
	s_nop 0
	v_pk_add_f32 v[64:65], v[64:65], v[68:69]
	s_nop 0
	v_add_f32_e32 v64, v64, v65
	s_nop 1
	v_add_f32_dpp v64, v64, v64 quad_perm:[1,0,3,2] row_mask:0xf bank_mask:0xf bound_ctrl:1
	s_nop 1
	v_add_f32_dpp v64, v64, v64 quad_perm:[2,3,0,1] row_mask:0xf bank_mask:0xf bound_ctrl:1
	s_nop 1
	v_add_f32_dpp v64, v64, v64 row_ror:4 row_mask:0xf bank_mask:0xf bound_ctrl:1
	s_nop 1
	v_add_f32_dpp v64, v64, v64 row_ror:8 row_mask:0xf bank_mask:0xf bound_ctrl:1
	s_nop 1
	v_add_f32_dpp v64, v64, v64 row_bcast:15 row_mask:0xa bank_mask:0xf
	s_nop 1
	v_add_f32_dpp v64, v64, v64 row_bcast:31 row_mask:0xc bank_mask:0xf
	s_nop 0
	v_readlane_b32 s98, v64, 63
	v_cmp_eq_u32_e64 s[100:101], s3, v254
	s_nop 0
	v_mov_b32_e32 v66, s98
	v_mul_f32_e32 v66, 0x3a800000, v66
	s_nop 0
	v_cndmask_b32_e64 v252, v252, v66, s[100:101]
	v_pk_add_f32 v[48:49], v[48:49], v[66:67] op_sel_hi:[1,0] neg_lo:[0,1] neg_hi:[0,1]
	v_pk_add_f32 v[50:51], v[50:51], v[66:67] op_sel_hi:[1,0] neg_lo:[0,1] neg_hi:[0,1]
	v_pk_add_f32 v[52:53], v[52:53], v[66:67] op_sel_hi:[1,0] neg_lo:[0,1] neg_hi:[0,1]
	v_pk_add_f32 v[54:55], v[54:55], v[66:67] op_sel_hi:[1,0] neg_lo:[0,1] neg_hi:[0,1]
	v_pk_add_f32 v[56:57], v[56:57], v[66:67] op_sel_hi:[1,0] neg_lo:[0,1] neg_hi:[0,1]
	v_pk_add_f32 v[58:59], v[58:59], v[66:67] op_sel_hi:[1,0] neg_lo:[0,1] neg_hi:[0,1]
	v_pk_add_f32 v[60:61], v[60:61], v[66:67] op_sel_hi:[1,0] neg_lo:[0,1] neg_hi:[0,1]
	v_pk_add_f32 v[62:63], v[62:63], v[66:67] op_sel_hi:[1,0] neg_lo:[0,1] neg_hi:[0,1]
	v_pk_mul_f32 v[68:69], v[48:49], v[48:49]
	v_pk_mul_f32 v[70:71], v[50:51], v[50:51]
	v_pk_fma_f32 v[68:69], v[52:53], v[52:53], v[68:69]
	v_pk_fma_f32 v[70:71], v[54:55], v[54:55], v[70:71]
	v_pk_fma_f32 v[68:69], v[56:57], v[56:57], v[68:69]
	v_pk_fma_f32 v[70:71], v[58:59], v[58:59], v[70:71]
	v_pk_fma_f32 v[68:69], v[60:61], v[60:61], v[68:69]
	v_pk_fma_f32 v[70:71], v[62:63], v[62:63], v[70:71]
	s_nop 0
	v_pk_add_f32 v[68:69], v[68:69], v[70:71]
	s_nop 0
	v_add_f32_e32 v68, v68, v69
	s_nop 1
	v_add_f32_dpp v68, v68, v68 quad_perm:[1,0,3,2] row_mask:0xf bank_mask:0xf bound_ctrl:1
	s_nop 1
	v_add_f32_dpp v68, v68, v68 quad_perm:[2,3,0,1] row_mask:0xf bank_mask:0xf bound_ctrl:1
	s_nop 1
	v_add_f32_dpp v68, v68, v68 row_ror:4 row_mask:0xf bank_mask:0xf bound_ctrl:1
	s_nop 1
	v_add_f32_dpp v68, v68, v68 row_ror:8 row_mask:0xf bank_mask:0xf bound_ctrl:1
	s_nop 1
	v_add_f32_dpp v68, v68, v68 row_bcast:15 row_mask:0xa bank_mask:0xf
	s_nop 1
	v_add_f32_dpp v68, v68, v68 row_bcast:31 row_mask:0xc bank_mask:0xf
	s_nop 0
	v_readlane_b32 s99, v68, 63
	s_nop 1
	v_mov_b32_e32 v70, s99
	v_fmamk_f32 v70, v70, 0x3a800000, v138
	v_rsq_f32_e32 v70, v70
	s_nop 0
	v_cndmask_b32_e64 v253, v253, v70, s[100:101]
	v_pk_mul_f32 v[48:49], v[48:49], v[70:71] op_sel_hi:[1,0]
	v_pk_mul_f32 v[50:51], v[50:51], v[70:71] op_sel_hi:[1,0]
	v_pk_mul_f32 v[52:53], v[52:53], v[70:71] op_sel_hi:[1,0]
	v_pk_mul_f32 v[54:55], v[54:55], v[70:71] op_sel_hi:[1,0]
	v_pk_mul_f32 v[56:57], v[56:57], v[70:71] op_sel_hi:[1,0]
	v_pk_mul_f32 v[58:59], v[58:59], v[70:71] op_sel_hi:[1,0]
	v_pk_mul_f32 v[60:61], v[60:61], v[70:71] op_sel_hi:[1,0]
	v_pk_mul_f32 v[62:63], v[62:63], v[70:71] op_sel_hi:[1,0]
	v_pk_fma_f32 v[48:49], v[214:215], v[48:49], v[230:231]
	v_pk_fma_f32 v[50:51], v[216:217], v[50:51], v[232:233]
	v_pk_fma_f32 v[52:53], v[218:219], v[52:53], v[234:235]
	v_pk_fma_f32 v[54:55], v[220:221], v[54:55], v[236:237]
	v_pk_fma_f32 v[56:57], v[222:223], v[56:57], v[238:239]
	v_pk_fma_f32 v[58:59], v[224:225], v[58:59], v[240:241]
	v_pk_fma_f32 v[60:61], v[226:227], v[60:61], v[242:243]
	v_pk_fma_f32 v[62:63], v[228:229], v[62:63], v[244:245]
	s_nop 0
	v_cvt_pk_bf16_f32 v64, v48, v49
	v_cvt_pk_bf16_f32 v65, v50, v51
	v_pk_mul_f32 v[48:49], v[48:49], v[44:45] op_sel_hi:[1,0]
	v_pk_mul_f32 v[50:51], v[50:51], v[44:45] op_sel_hi:[1,0]
	global_store_dwordx2 v[28:29], v[64:65], off offset:1024
	v_cvt_pk_fp8_f32 v72, v48, v49
	v_cvt_pk_fp8_f32 v72, v50, v51 op_sel:[0,0,1]
	global_store_dword v[26:27], v72, off offset:512
	v_cvt_pk_bf16_f32 v66, v52, v53
	v_cvt_pk_bf16_f32 v67, v54, v55
	v_pk_mul_f32 v[52:53], v[52:53], v[44:45] op_sel_hi:[1,0]
	v_pk_mul_f32 v[54:55], v[54:55], v[44:45] op_sel_hi:[1,0]
	global_store_dwordx2 v[28:29], v[66:67], off offset:1536
	v_cvt_pk_fp8_f32 v73, v52, v53
	v_cvt_pk_fp8_f32 v73, v54, v55 op_sel:[0,0,1]
	global_store_dword v[26:27], v73, off offset:768
	v_cvt_pk_bf16_f32 v68, v56, v57
	v_cvt_pk_bf16_f32 v69, v58, v59
	v_pk_mul_f32 v[56:57], v[56:57], v[44:45] op_sel_hi:[1,0]
	v_pk_mul_f32 v[58:59], v[58:59], v[44:45] op_sel_hi:[1,0]
	global_store_dwordx2 v[28:29], v[68:69], off offset:2048
	v_cvt_pk_fp8_f32 v74, v56, v57
	v_cvt_pk_fp8_f32 v74, v58, v59 op_sel:[0,0,1]
	global_store_dword v[26:27], v74, off offset:1024
	v_cvt_pk_bf16_f32 v70, v60, v61
	v_cvt_pk_bf16_f32 v71, v62, v63
	v_pk_mul_f32 v[60:61], v[60:61], v[44:45] op_sel_hi:[1,0]
	v_pk_mul_f32 v[62:63], v[62:63], v[44:45] op_sel_hi:[1,0]
	global_store_dwordx2 v[28:29], v[70:71], off offset:2560
	v_cvt_pk_fp8_f32 v75, v60, v61
	v_cvt_pk_fp8_f32 v75, v62, v63 op_sel:[0,0,1]
	global_store_dword v[26:27], v75, off offset:1280
	s_add_i32 s3, s3, 1
	s_mov_b64 s[100:101], 0x1000
	v_lshl_add_u64 v[28:29], v[28:29], 0, s[100:101]
	s_mov_b64 s[100:101], 0x800
	v_lshl_add_u64 v[26:27], v[26:27], 0, s[100:101]
	s_cmp_lg_u32 s3, 32
	s_cbranch_scc1 .Lln1_pair
	s_waitcnt vmcnt(8)
	s_mov_b64 s[54:55], 0
	s_barrier
	s_add_u32 s50, s96, s54
	s_addc_u32 s51, s97, s55
	s_add_u32 s3, s50, s58
	s_addc_u32 s16, s51, s59
	s_add_u32 s56, s3, 0x8000000
	s_addc_u32 s57, s16, 0
	s_add_u32 s52, s3, 0x28000000
	s_addc_u32 s53, s16, 0
	s_add_u32 s16, s50, 0x1600000
	s_addc_u32 s66, s51, 0
	s_add_u32 s3, s54, s46
	s_addc_u32 s59, s55, s47
	s_add_u32 s58, s96, s3
	s_addc_u32 s59, s97, s59
	s_mov_b32 s67, 0
	s_mov_b64 s[60:61], s[50:51]
